# SwiGLU epilogue rescheduled as a 4-deep software pipeline over the row groups with v_exp/v_rcp strictly alternating with packed mul/fma/convert ops (v31 base)
# speedup vs baseline: 1.0048x; 1.0040x over previous
; __device__ __forceinline__ float ld_agent(const rss_t* p) { return (float)__hip_atomic_load(p, __ATOMIC_RELAXED, __HIP_MEMORY_SCOPE_AGENT) * (1.0f / 16777216.0f); }
; __device__ __forceinline__ rss_t rss_fix(float ss) { return (rss_t)(ss * 16777216.0f); }
; __device__ __forceinline__ float rstd_of(const rss_t* rowss, int row) { return __builtin_amdgcn_rsqf(ld_agent(rowss + row) * (1.0f / 1024.0f) + 1e-6f); }
; __device__ __forceinline__ unsigned silu_pk(f32x2 g, f32x2 u, float k1, float k2) {
;     const f32x2 t = g * k1; f32x2 ex; ex.x = __builtin_amdgcn_exp2f(t.x); ex.y = __builtin_amdgcn_exp2f(t.y);
;     const f32x2 d = ex + 1.0f; f32x2 r; r.x = __builtin_amdgcn_rcpf(d.x); r.y = __builtin_amdgcn_rcpf(d.y);
;     const f32x2 o = (g * u) * (r * k2);
;     return cvt_pk_bf16(o.x, o.y);
; }
; __device__ __forceinline__ float silu_mul(float g, float u) { return g * __builtin_amdgcn_rcpf(1.0f + __builtin_amdgcn_exp2f(-1.4426950408889634f * g)) * u; }
;     __device__ __forceinline__ void operator()(const f32x4 (&acc)[2][2][4][2], const Unit& u, int wr, int wc, int fr, int fq) const {
;         const int row0 = u.pm * BM + wr * 64 + fr, col0 = u.pn * HALF + wc * 32 + 8 * fq;
;         float ssq[2][4];
; #pragma unroll
;         for (int ai = 0; ai < 2; ++ai)
; #pragma unroll
;             for (int m = 0; m < 4; ++m) ssq[ai][m] = ld_agent(rowss + row0 + ai * HALF + m * 16);
; #pragma unroll
;         for (int ai = 0; ai < 2; ++ai)
; #pragma unroll
;             for (int m = 0; m < 4; ++m) {
;                 const int row = row0 + ai * HALF + m * 16; const float rs = __builtin_amdgcn_rsqf(ssq[ai][m] * (1.0f / 1024.0f) + 1e-6f);
;                 const float k1 = -1.4426950408889634f * rs, k2 = rs * rs;
;                 u32x4 w;
; #pragma unroll
;                 for (int n = 0; n < 2; ++n) {
;                     const f32x4 gv = acc[ai][0][m][n], uv = acc[ai][1][m][n];
;                     const unsigned lo = silu_pk((f32x2){gv[0], gv[1]}, (f32x2){uv[0], uv[1]}, k1, k2), hi = silu_pk((f32x2){gv[2], gv[3]}, (f32x2){uv[2], uv[3]}, k1, k2);
;                     if (n == 0) { w.x = lo; w.y = hi; } else { w.z = lo; w.w = hi; }
;                 }
;                 *(u32x4*)(O + (size_t)row * ldc + col0) = w;
.LBB0_235:
	v_lshl_add_u32 v144, s36, 8, v146
	v_ashrrev_i32_e32 v145, 31, v144
	v_lshl_add_u64 v[226:227], v[144:145], 3, s[8:9]
	global_load_dwordx2 v[154:155], v[226:227], off sc1
	global_load_dwordx2 v[156:157], v[226:227], off offset:128 sc1
	global_load_dwordx2 v[158:159], v[226:227], off offset:256 sc1
	global_load_dwordx2 v[160:161], v[226:227], off offset:384 sc1
	global_load_dwordx2 v[162:163], v[226:227], off offset:1024 sc1
	global_load_dwordx2 v[164:165], v[226:227], off offset:1152 sc1
	global_load_dwordx2 v[166:167], v[226:227], off offset:1280 sc1
	global_load_dwordx2 v[168:169], v[226:227], off offset:1408 sc1
	v_pk_mul_f32 v[124:125], v[120:121], v[124:125]
	v_pk_mul_f32 v[126:127], v[122:123], v[126:127]
	v_pk_mul_f32 v[112:113], v[116:117], v[112:113]
	v_pk_mul_f32 v[114:115], v[118:119], v[114:115]
	v_pk_mul_f32 v[104:105], v[108:109], v[104:105]
	v_pk_mul_f32 v[106:107], v[110:111], v[106:107]
	v_pk_mul_f32 v[96:97], v[100:101], v[96:97]
	v_pk_mul_f32 v[98:99], v[102:103], v[98:99]
	v_pk_mul_f32 v[88:89], v[92:93], v[88:89]
	v_pk_mul_f32 v[90:91], v[94:95], v[90:91]
	v_pk_mul_f32 v[80:81], v[84:85], v[80:81]
	v_pk_mul_f32 v[82:83], v[86:87], v[82:83]
	v_pk_mul_f32 v[72:73], v[76:77], v[72:73]
	v_pk_mul_f32 v[74:75], v[78:79], v[74:75]
	v_pk_mul_f32 v[64:65], v[68:69], v[64:65]
	v_pk_mul_f32 v[66:67], v[70:71], v[66:67]
	v_pk_mul_f32 v[56:57], v[60:61], v[56:57]
	v_pk_mul_f32 v[58:59], v[62:63], v[58:59]
	v_pk_mul_f32 v[48:49], v[52:53], v[48:49]
	v_pk_mul_f32 v[50:51], v[54:55], v[50:51]
	v_pk_mul_f32 v[40:41], v[44:45], v[40:41]
	v_pk_mul_f32 v[42:43], v[46:47], v[42:43]
	v_pk_mul_f32 v[32:33], v[36:37], v[32:33]
	v_pk_mul_f32 v[34:35], v[38:39], v[34:35]
	v_pk_mul_f32 v[24:25], v[28:29], v[24:25]
	v_pk_mul_f32 v[26:27], v[30:31], v[26:27]
	v_pk_mul_f32 v[16:17], v[20:21], v[16:17]
	v_pk_mul_f32 v[18:19], v[22:23], v[18:19]
	v_pk_mul_f32 v[8:9], v[12:13], v[8:9]
	v_pk_mul_f32 v[10:11], v[14:15], v[10:11]
	v_pk_mul_f32 v[0:1], v[4:5], v[0:1]
	v_pk_mul_f32 v[2:3], v[6:7], v[2:3]
	v_lshl_or_b32 v230, s63, 7, v148
	v_ashrrev_i32_e32 v231, 31, v230
	v_mov_b64_e32 v[232:233], s[12:13]
	v_lshlrev_b64 v[230:231], 1, v[230:231]
	v_mad_i64_i32 v[228:229], s[38:39], v144, s59, v[232:233]
	s_mov_b64 s[96:97], 0x16000
	s_mov_b64 s[98:99], 0x6e000
	v_lshl_add_u64 v[228:229], v[228:229], 0, v[230:231]
	s_andn2_b64 vcc, exec, s[4:5]
	s_mov_b64 s[4:5], -1
	s_waitcnt vmcnt(0)
	v_cvt_f32_u32_e32 v186, v155
	v_cvt_f32_u32_e32 v188, v157
	v_cvt_f32_u32_e32 v190, v159
	v_cvt_f32_u32_e32 v192, v161
	v_cvt_f32_u32_e32 v194, v163
	v_cvt_f32_u32_e32 v196, v165
	v_cvt_f32_u32_e32 v198, v167
	v_cvt_f32_u32_e32 v200, v169
	v_cvt_f32_u32_e32 v187, v154
	v_cvt_f32_u32_e32 v189, v156
	v_cvt_f32_u32_e32 v191, v158
	v_cvt_f32_u32_e32 v193, v160
	v_cvt_f32_u32_e32 v195, v162
	v_cvt_f32_u32_e32 v197, v164
	v_cvt_f32_u32_e32 v199, v166
	v_cvt_f32_u32_e32 v201, v168
	v_fmamk_f32 v186, v186, 0x4f800000, v187
	v_fmamk_f32 v188, v188, 0x4f800000, v189
	v_fmamk_f32 v190, v190, 0x4f800000, v191
	v_fmamk_f32 v192, v192, 0x4f800000, v193
	v_fmamk_f32 v194, v194, 0x4f800000, v195
	v_fmamk_f32 v196, v196, 0x4f800000, v197
	v_fmamk_f32 v198, v198, 0x4f800000, v199
	v_fmamk_f32 v200, v200, 0x4f800000, v201
	v_fmamk_f32 v171, v186, 0x2e800000, v152
	v_fmamk_f32 v173, v188, 0x2e800000, v152
	v_fmamk_f32 v175, v190, 0x2e800000, v152
	v_fmamk_f32 v177, v192, 0x2e800000, v152
	v_fmamk_f32 v179, v194, 0x2e800000, v152
	v_fmamk_f32 v181, v196, 0x2e800000, v152
	v_fmamk_f32 v183, v198, 0x2e800000, v152
	v_fmamk_f32 v185, v200, 0x2e800000, v152
	v_rsq_f32_e32 v170, v171
	v_rsq_f32_e32 v172, v173
	v_rsq_f32_e32 v174, v175
	v_rsq_f32_e32 v176, v177
	v_rsq_f32_e32 v178, v179
	v_rsq_f32_e32 v180, v181
	v_rsq_f32_e32 v182, v183
	v_rsq_f32_e32 v184, v185
	v_mul_f32_e32 v170, 0xbfb8aa3b, v170
	v_mul_f32_e32 v172, 0xbfb8aa3b, v172
	v_mul_f32_e32 v174, 0xbfb8aa3b, v174
	v_mul_f32_e32 v176, 0xbfb8aa3b, v176
	v_mul_f32_e32 v178, 0xbfb8aa3b, v178
	v_mul_f32_e32 v180, 0xbfb8aa3b, v180
	v_mul_f32_e32 v182, 0xbfb8aa3b, v182
	v_mul_f32_e32 v184, 0xbfb8aa3b, v184
	v_pk_mul_f32 v[186:187], v[120:121], v[170:171] op_sel_hi:[1,0]
	v_pk_mul_f32 v[188:189], v[122:123], v[170:171] op_sel_hi:[1,0]
	v_pk_mul_f32 v[190:191], v[116:117], v[170:171] op_sel_hi:[1,0]
	v_pk_mul_f32 v[192:193], v[118:119], v[170:171] op_sel_hi:[1,0]
	v_exp_f32_e32 v186, v186
	v_exp_f32_e32 v187, v187
	v_exp_f32_e32 v188, v188
	v_exp_f32_e32 v189, v189
	v_exp_f32_e32 v190, v190
	v_exp_f32_e32 v191, v191
	v_exp_f32_e32 v192, v192
	v_exp_f32_e32 v193, v193
	v_pk_mul_f32 v[194:195], v[108:109], v[172:173] op_sel_hi:[1,0]
	v_pk_mul_f32 v[196:197], v[110:111], v[172:173] op_sel_hi:[1,0]
	v_pk_mul_f32 v[198:199], v[100:101], v[172:173] op_sel_hi:[1,0]
	v_pk_mul_f32 v[200:201], v[102:103], v[172:173] op_sel_hi:[1,0]
	v_exp_f32_e32 v194, v194
	v_pk_fma_f32 v[186:187], v[186:187], v[170:171], v[170:171] op_sel:[0,1,1] op_sel_hi:[1,1,1]
	v_exp_f32_e32 v195, v195
	v_pk_fma_f32 v[188:189], v[188:189], v[170:171], v[170:171] op_sel:[0,1,1] op_sel_hi:[1,1,1]
	v_exp_f32_e32 v196, v196
	v_pk_fma_f32 v[190:191], v[190:191], v[170:171], v[170:171] op_sel:[0,1,1] op_sel_hi:[1,1,1]
	v_exp_f32_e32 v197, v197
	v_pk_fma_f32 v[192:193], v[192:193], v[170:171], v[170:171] op_sel:[0,1,1] op_sel_hi:[1,1,1]
	v_exp_f32_e32 v198, v198
	v_exp_f32_e32 v199, v199
	v_exp_f32_e32 v200, v200
	v_exp_f32_e32 v201, v201
	v_rcp_f32_e32 v186, v186
	v_pk_mul_f32 v[202:203], v[92:93], v[174:175] op_sel_hi:[1,0]
	v_rcp_f32_e32 v187, v187
	v_pk_mul_f32 v[204:205], v[94:95], v[174:175] op_sel_hi:[1,0]
	v_rcp_f32_e32 v188, v188
	v_pk_mul_f32 v[206:207], v[84:85], v[174:175] op_sel_hi:[1,0]
; __device__ __forceinline__ unsigned cvt_pk_bf16(float lo, float hi) { unsigned r; asm volatile("v_cvt_pk_bf16_f32 %0, %1, %2" : "=v"(r) : "v"(lo), "v"(hi)); return r; }
; __device__ __forceinline__ unsigned silu_pk(f32x2 g, f32x2 u, float k1, float k2) {
;     const f32x2 t = g * k1; f32x2 ex; ex.x = __builtin_amdgcn_exp2f(t.x); ex.y = __builtin_amdgcn_exp2f(t.y);
;     const f32x2 d = ex + 1.0f; f32x2 r; r.x = __builtin_amdgcn_rcpf(d.x); r.y = __builtin_amdgcn_rcpf(d.y);
;     const f32x2 o = (g * u) * (r * k2);
;     return cvt_pk_bf16(o.x, o.y);
;     __device__ __forceinline__ void operator()(const f32x4 (&acc)[2][2][4][2], const Unit& u, int wr, int wc, int fr, int fq) const {
;     ...
;             for (int m = 0; m < 4; ++m) {
;                 const int row = row0 + ai * HALF + m * 16; const float rs = __builtin_amdgcn_rsqf(ssq[ai][m] * (1.0f / 1024.0f) + 1e-6f);
;                 const float k1 = -1.4426950408889634f * rs, k2 = rs * rs;
;                 u32x4 w;
; #pragma unroll
;                 for (int n = 0; n < 2; ++n) {
;                     const f32x4 gv = acc[ai][0][m][n], uv = acc[ai][1][m][n];
;                     const unsigned lo = silu_pk((f32x2){gv[0], gv[1]}, (f32x2){uv[0], uv[1]}, k1, k2), hi = silu_pk((f32x2){gv[2], gv[3]}, (f32x2){uv[2], uv[3]}, k1, k2);
;                     if (n == 0) { w.x = lo; w.y = hi; } else { w.z = lo; w.w = hi; }
;                 }
;                 *(u32x4*)(O + (size_t)row * ldc + col0) = w;
	v_rcp_f32_e32 v189, v189
	v_pk_mul_f32 v[208:209], v[86:87], v[174:175] op_sel_hi:[1,0]
	v_rcp_f32_e32 v190, v190
	v_rcp_f32_e32 v191, v191
	v_rcp_f32_e32 v192, v192
	v_rcp_f32_e32 v193, v193
	v_exp_f32_e32 v202, v202
	v_pk_fma_f32 v[194:195], v[194:195], v[172:173], v[172:173] op_sel:[0,1,1] op_sel_hi:[1,1,1]
	v_exp_f32_e32 v203, v203
	v_pk_fma_f32 v[196:197], v[196:197], v[172:173], v[172:173] op_sel:[0,1,1] op_sel_hi:[1,1,1]
	v_exp_f32_e32 v204, v204
	v_pk_fma_f32 v[198:199], v[198:199], v[172:173], v[172:173] op_sel:[0,1,1] op_sel_hi:[1,1,1]
	v_exp_f32_e32 v205, v205
	v_pk_fma_f32 v[200:201], v[200:201], v[172:173], v[172:173] op_sel:[0,1,1] op_sel_hi:[1,1,1]
	v_exp_f32_e32 v206, v206
	v_pk_mul_f32 v[186:187], v[124:125], v[186:187]
	v_exp_f32_e32 v207, v207
	v_pk_mul_f32 v[188:189], v[126:127], v[188:189]
	v_exp_f32_e32 v208, v208
	v_pk_mul_f32 v[190:191], v[112:113], v[190:191]
	v_exp_f32_e32 v209, v209
	v_pk_mul_f32 v[192:193], v[114:115], v[192:193]
	v_rcp_f32_e32 v194, v194
	v_cvt_pk_bf16_f32 v218, v186, v187
	v_rcp_f32_e32 v195, v195
	v_cvt_pk_bf16_f32 v219, v188, v189
	v_rcp_f32_e32 v196, v196
	v_cvt_pk_bf16_f32 v220, v190, v191
	v_rcp_f32_e32 v197, v197
	v_cvt_pk_bf16_f32 v221, v192, v193
	v_rcp_f32_e32 v198, v198
	global_store_dwordx4 v[228:229], v[218:221], off
	v_rcp_f32_e32 v199, v199
	v_lshl_add_u64 v[228:229], v[228:229], 0, s[96:97]
	v_rcp_f32_e32 v200, v200
	v_pk_mul_f32 v[210:211], v[76:77], v[176:177] op_sel_hi:[1,0]
	v_rcp_f32_e32 v201, v201
	v_pk_mul_f32 v[212:213], v[78:79], v[176:177] op_sel_hi:[1,0]
	v_pk_mul_f32 v[214:215], v[68:69], v[176:177] op_sel_hi:[1,0]
	v_pk_mul_f32 v[216:217], v[70:71], v[176:177] op_sel_hi:[1,0]
	v_exp_f32_e32 v210, v210
	v_pk_fma_f32 v[202:203], v[202:203], v[174:175], v[174:175] op_sel:[0,1,1] op_sel_hi:[1,1,1]
	v_exp_f32_e32 v211, v211
	v_pk_fma_f32 v[204:205], v[204:205], v[174:175], v[174:175] op_sel:[0,1,1] op_sel_hi:[1,1,1]
	v_exp_f32_e32 v212, v212
	v_pk_fma_f32 v[206:207], v[206:207], v[174:175], v[174:175] op_sel:[0,1,1] op_sel_hi:[1,1,1]
	v_exp_f32_e32 v213, v213
	v_pk_fma_f32 v[208:209], v[208:209], v[174:175], v[174:175] op_sel:[0,1,1] op_sel_hi:[1,1,1]
	v_exp_f32_e32 v214, v214
	v_pk_mul_f32 v[194:195], v[104:105], v[194:195]
	v_exp_f32_e32 v215, v215
	v_pk_mul_f32 v[196:197], v[106:107], v[196:197]
	v_exp_f32_e32 v216, v216
	v_pk_mul_f32 v[198:199], v[96:97], v[198:199]
	v_exp_f32_e32 v217, v217
	v_pk_mul_f32 v[200:201], v[98:99], v[200:201]
	v_rcp_f32_e32 v202, v202
	v_cvt_pk_bf16_f32 v222, v194, v195
	v_rcp_f32_e32 v203, v203
	v_cvt_pk_bf16_f32 v223, v196, v197
	v_rcp_f32_e32 v204, v204
	v_cvt_pk_bf16_f32 v224, v198, v199
	v_rcp_f32_e32 v205, v205
	v_cvt_pk_bf16_f32 v225, v200, v201
	v_rcp_f32_e32 v206, v206
	global_store_dwordx4 v[228:229], v[222:225], off
	v_rcp_f32_e32 v207, v207
	v_lshl_add_u64 v[228:229], v[228:229], 0, s[96:97]
	v_rcp_f32_e32 v208, v208
	v_pk_mul_f32 v[186:187], v[60:61], v[178:179] op_sel_hi:[1,0]
	v_rcp_f32_e32 v209, v209
	v_pk_mul_f32 v[188:189], v[62:63], v[178:179] op_sel_hi:[1,0]
	v_pk_mul_f32 v[190:191], v[52:53], v[178:179] op_sel_hi:[1,0]
	v_pk_mul_f32 v[192:193], v[54:55], v[178:179] op_sel_hi:[1,0]
	v_exp_f32_e32 v186, v186
	v_pk_fma_f32 v[210:211], v[210:211], v[176:177], v[176:177] op_sel:[0,1,1] op_sel_hi:[1,1,1]
	v_exp_f32_e32 v187, v187
	v_pk_fma_f32 v[212:213], v[212:213], v[176:177], v[176:177] op_sel:[0,1,1] op_sel_hi:[1,1,1]
	v_exp_f32_e32 v188, v188
	v_pk_fma_f32 v[214:215], v[214:215], v[176:177], v[176:177] op_sel:[0,1,1] op_sel_hi:[1,1,1]
	v_exp_f32_e32 v189, v189
	v_pk_fma_f32 v[216:217], v[216:217], v[176:177], v[176:177] op_sel:[0,1,1] op_sel_hi:[1,1,1]
	v_exp_f32_e32 v190, v190
	v_pk_mul_f32 v[202:203], v[88:89], v[202:203]
	v_exp_f32_e32 v191, v191
	v_pk_mul_f32 v[204:205], v[90:91], v[204:205]
	v_exp_f32_e32 v192, v192
	v_pk_mul_f32 v[206:207], v[80:81], v[206:207]
	v_exp_f32_e32 v193, v193
	v_pk_mul_f32 v[208:209], v[82:83], v[208:209]
	v_rcp_f32_e32 v210, v210
	v_cvt_pk_bf16_f32 v218, v202, v203
	v_rcp_f32_e32 v211, v211
	v_cvt_pk_bf16_f32 v219, v204, v205
	v_rcp_f32_e32 v212, v212
	v_cvt_pk_bf16_f32 v220, v206, v207
	v_rcp_f32_e32 v213, v213
	v_cvt_pk_bf16_f32 v221, v208, v209
	v_rcp_f32_e32 v214, v214
	global_store_dwordx4 v[228:229], v[218:221], off
	v_rcp_f32_e32 v215, v215
	v_lshl_add_u64 v[228:229], v[228:229], 0, s[96:97]
	v_rcp_f32_e32 v216, v216
	v_pk_mul_f32 v[194:195], v[44:45], v[180:181] op_sel_hi:[1,0]
	v_rcp_f32_e32 v217, v217
	v_pk_mul_f32 v[196:197], v[46:47], v[180:181] op_sel_hi:[1,0]
	v_pk_mul_f32 v[198:199], v[36:37], v[180:181] op_sel_hi:[1,0]
	v_pk_mul_f32 v[200:201], v[38:39], v[180:181] op_sel_hi:[1,0]
	v_exp_f32_e32 v194, v194
	v_pk_fma_f32 v[186:187], v[186:187], v[178:179], v[178:179] op_sel:[0,1,1] op_sel_hi:[1,1,1]
	v_exp_f32_e32 v195, v195
	v_pk_fma_f32 v[188:189], v[188:189], v[178:179], v[178:179] op_sel:[0,1,1] op_sel_hi:[1,1,1]
	v_exp_f32_e32 v196, v196
	v_pk_fma_f32 v[190:191], v[190:191], v[178:179], v[178:179] op_sel:[0,1,1] op_sel_hi:[1,1,1]
	v_exp_f32_e32 v197, v197
	v_pk_fma_f32 v[192:193], v[192:193], v[178:179], v[178:179] op_sel:[0,1,1] op_sel_hi:[1,1,1]
	v_exp_f32_e32 v198, v198
; __device__ __forceinline__ unsigned cvt_pk_bf16(float lo, float hi) { unsigned r; asm volatile("v_cvt_pk_bf16_f32 %0, %1, %2" : "=v"(r) : "v"(lo), "v"(hi)); return r; }
; #define PG8_BAR __builtin_amdgcn_s_barrier()
; __device__ __forceinline__ unsigned silu_pk(f32x2 g, f32x2 u, float k1, float k2) {
;     const f32x2 t = g * k1; f32x2 ex; ex.x = __builtin_amdgcn_exp2f(t.x); ex.y = __builtin_amdgcn_exp2f(t.y);
;     const f32x2 d = ex + 1.0f; f32x2 r; r.x = __builtin_amdgcn_rcpf(d.x); r.y = __builtin_amdgcn_rcpf(d.y);
;     const f32x2 o = (g * u) * (r * k2);
;     return cvt_pk_bf16(o.x, o.y);
;     __device__ __forceinline__ void operator()(const f32x4 (&acc)[2][2][4][2], const Unit& u, int wr, int wc, int fr, int fq) const {
;     ...
;             for (int m = 0; m < 4; ++m) {
;                 const int row = row0 + ai * HALF + m * 16; const float rs = __builtin_amdgcn_rsqf(ssq[ai][m] * (1.0f / 1024.0f) + 1e-6f);
;                 const float k1 = -1.4426950408889634f * rs, k2 = rs * rs;
;                 u32x4 w;
; #pragma unroll
;                 for (int n = 0; n < 2; ++n) {
;                     const f32x4 gv = acc[ai][0][m][n], uv = acc[ai][1][m][n];
;                     const unsigned lo = silu_pk((f32x2){gv[0], gv[1]}, (f32x2){uv[0], uv[1]}, k1, k2), hi = silu_pk((f32x2){gv[2], gv[3]}, (f32x2){uv[2], uv[3]}, k1, k2);
;                     if (n == 0) { w.x = lo; w.y = hi; } else { w.z = lo; w.w = hi; }
;                 }
;                 *(u32x4*)(O + (size_t)row * ldc + col0) = w;
; template <class Epi, class Sched, bool ALIGN_EPI = false, bool SP2 = false>
; __device__ __forceinline__ void gemm_phase(PG8_LAS unsigned char* lds, const Gemm g, const Sched& S, const Epi& E) {
;     ...
;         if constexpr (ALIGN_EPI) { if (wr == 1) PG8_BAR; }
	v_pk_mul_f32 v[210:211], v[72:73], v[210:211]
	v_exp_f32_e32 v199, v199
	v_pk_mul_f32 v[212:213], v[74:75], v[212:213]
	v_exp_f32_e32 v200, v200
	v_pk_mul_f32 v[214:215], v[64:65], v[214:215]
	v_exp_f32_e32 v201, v201
	v_pk_mul_f32 v[216:217], v[66:67], v[216:217]
	v_rcp_f32_e32 v186, v186
	v_cvt_pk_bf16_f32 v222, v210, v211
	v_rcp_f32_e32 v187, v187
	v_cvt_pk_bf16_f32 v223, v212, v213
	v_rcp_f32_e32 v188, v188
	v_cvt_pk_bf16_f32 v224, v214, v215
	v_rcp_f32_e32 v189, v189
	v_cvt_pk_bf16_f32 v225, v216, v217
	v_rcp_f32_e32 v190, v190
	global_store_dwordx4 v[228:229], v[222:225], off
	v_rcp_f32_e32 v191, v191
	v_lshl_add_u64 v[228:229], v[228:229], 0, s[98:99]
	v_rcp_f32_e32 v192, v192
	v_pk_mul_f32 v[202:203], v[28:29], v[182:183] op_sel_hi:[1,0]
	v_rcp_f32_e32 v193, v193
	v_pk_mul_f32 v[204:205], v[30:31], v[182:183] op_sel_hi:[1,0]
	v_pk_mul_f32 v[206:207], v[20:21], v[182:183] op_sel_hi:[1,0]
	v_pk_mul_f32 v[208:209], v[22:23], v[182:183] op_sel_hi:[1,0]
	v_exp_f32_e32 v202, v202
	v_pk_fma_f32 v[194:195], v[194:195], v[180:181], v[180:181] op_sel:[0,1,1] op_sel_hi:[1,1,1]
	v_exp_f32_e32 v203, v203
	v_pk_fma_f32 v[196:197], v[196:197], v[180:181], v[180:181] op_sel:[0,1,1] op_sel_hi:[1,1,1]
	v_exp_f32_e32 v204, v204
	v_pk_fma_f32 v[198:199], v[198:199], v[180:181], v[180:181] op_sel:[0,1,1] op_sel_hi:[1,1,1]
	v_exp_f32_e32 v205, v205
	v_pk_fma_f32 v[200:201], v[200:201], v[180:181], v[180:181] op_sel:[0,1,1] op_sel_hi:[1,1,1]
	v_exp_f32_e32 v206, v206
	v_pk_mul_f32 v[186:187], v[56:57], v[186:187]
	v_exp_f32_e32 v207, v207
	v_pk_mul_f32 v[188:189], v[58:59], v[188:189]
	v_exp_f32_e32 v208, v208
	v_pk_mul_f32 v[190:191], v[48:49], v[190:191]
	v_exp_f32_e32 v209, v209
	v_pk_mul_f32 v[192:193], v[50:51], v[192:193]
	v_rcp_f32_e32 v194, v194
	v_cvt_pk_bf16_f32 v218, v186, v187
	v_rcp_f32_e32 v195, v195
	v_cvt_pk_bf16_f32 v219, v188, v189
	v_rcp_f32_e32 v196, v196
	v_cvt_pk_bf16_f32 v220, v190, v191
	v_rcp_f32_e32 v197, v197
	v_cvt_pk_bf16_f32 v221, v192, v193
	v_rcp_f32_e32 v198, v198
	global_store_dwordx4 v[228:229], v[218:221], off
	v_rcp_f32_e32 v199, v199
	v_lshl_add_u64 v[228:229], v[228:229], 0, s[96:97]
	v_rcp_f32_e32 v200, v200
	v_pk_mul_f32 v[210:211], v[12:13], v[184:185] op_sel_hi:[1,0]
	v_rcp_f32_e32 v201, v201
	v_pk_mul_f32 v[212:213], v[14:15], v[184:185] op_sel_hi:[1,0]
	v_pk_mul_f32 v[214:215], v[4:5], v[184:185] op_sel_hi:[1,0]
	v_pk_mul_f32 v[216:217], v[6:7], v[184:185] op_sel_hi:[1,0]
	v_exp_f32_e32 v210, v210
	v_pk_fma_f32 v[202:203], v[202:203], v[182:183], v[182:183] op_sel:[0,1,1] op_sel_hi:[1,1,1]
	v_exp_f32_e32 v211, v211
	v_pk_fma_f32 v[204:205], v[204:205], v[182:183], v[182:183] op_sel:[0,1,1] op_sel_hi:[1,1,1]
	v_exp_f32_e32 v212, v212
	v_pk_fma_f32 v[206:207], v[206:207], v[182:183], v[182:183] op_sel:[0,1,1] op_sel_hi:[1,1,1]
	v_exp_f32_e32 v213, v213
	v_pk_fma_f32 v[208:209], v[208:209], v[182:183], v[182:183] op_sel:[0,1,1] op_sel_hi:[1,1,1]
	v_exp_f32_e32 v214, v214
	v_pk_mul_f32 v[194:195], v[40:41], v[194:195]
	v_exp_f32_e32 v215, v215
	v_pk_mul_f32 v[196:197], v[42:43], v[196:197]
	v_exp_f32_e32 v216, v216
	v_pk_mul_f32 v[198:199], v[32:33], v[198:199]
	v_exp_f32_e32 v217, v217
	v_pk_mul_f32 v[200:201], v[34:35], v[200:201]
	v_rcp_f32_e32 v202, v202
	v_cvt_pk_bf16_f32 v222, v194, v195
	v_rcp_f32_e32 v203, v203
	v_cvt_pk_bf16_f32 v223, v196, v197
	v_rcp_f32_e32 v204, v204
	v_cvt_pk_bf16_f32 v224, v198, v199
	v_rcp_f32_e32 v205, v205
	v_cvt_pk_bf16_f32 v225, v200, v201
	v_rcp_f32_e32 v206, v206
	global_store_dwordx4 v[228:229], v[222:225], off
	v_rcp_f32_e32 v207, v207
	v_lshl_add_u64 v[228:229], v[228:229], 0, s[96:97]
	v_rcp_f32_e32 v208, v208
	v_rcp_f32_e32 v209, v209
	v_pk_fma_f32 v[210:211], v[210:211], v[184:185], v[184:185] op_sel:[0,1,1] op_sel_hi:[1,1,1]
	v_pk_fma_f32 v[212:213], v[212:213], v[184:185], v[184:185] op_sel:[0,1,1] op_sel_hi:[1,1,1]
	v_pk_fma_f32 v[214:215], v[214:215], v[184:185], v[184:185] op_sel:[0,1,1] op_sel_hi:[1,1,1]
	v_pk_fma_f32 v[216:217], v[216:217], v[184:185], v[184:185] op_sel:[0,1,1] op_sel_hi:[1,1,1]
	v_pk_mul_f32 v[202:203], v[24:25], v[202:203]
	v_pk_mul_f32 v[204:205], v[26:27], v[204:205]
	v_pk_mul_f32 v[206:207], v[16:17], v[206:207]
	v_pk_mul_f32 v[208:209], v[18:19], v[208:209]
	v_rcp_f32_e32 v210, v210
	v_cvt_pk_bf16_f32 v218, v202, v203
	v_rcp_f32_e32 v211, v211
	v_cvt_pk_bf16_f32 v219, v204, v205
	v_rcp_f32_e32 v212, v212
	v_cvt_pk_bf16_f32 v220, v206, v207
	v_rcp_f32_e32 v213, v213
	v_cvt_pk_bf16_f32 v221, v208, v209
	v_rcp_f32_e32 v214, v214
	global_store_dwordx4 v[228:229], v[218:221], off
	v_rcp_f32_e32 v215, v215
	v_lshl_add_u64 v[228:229], v[228:229], 0, s[96:97]
	v_rcp_f32_e32 v216, v216
	v_rcp_f32_e32 v217, v217
	v_pk_mul_f32 v[210:211], v[8:9], v[210:211]
	v_pk_mul_f32 v[212:213], v[10:11], v[212:213]
	v_pk_mul_f32 v[214:215], v[0:1], v[214:215]
	v_pk_mul_f32 v[216:217], v[2:3], v[216:217]
	v_cvt_pk_bf16_f32 v222, v210, v211
	v_cvt_pk_bf16_f32 v223, v212, v213
	v_cvt_pk_bf16_f32 v224, v214, v215
	v_cvt_pk_bf16_f32 v225, v216, v217
	global_store_dwordx4 v[228:229], v[222:225], off
	s_cbranch_vccnz .LBB0_228
	s_andn2_b64 vcc, exec, s[6:7]
	s_cbranch_vccnz .LBB0_227
	s_barrier
	s_branch .LBB0_227

; __device__ __forceinline__ float ld_agent(const rss_t* p) { return (float)__hip_atomic_load(p, __ATOMIC_RELAXED, __HIP_MEMORY_SCOPE_AGENT) * (1.0f / 16777216.0f); }
; __device__ __forceinline__ rss_t rss_fix(float ss) { return (rss_t)(ss * 16777216.0f); }
; __device__ __forceinline__ float rstd_of(const rss_t* rowss, int row) { return __builtin_amdgcn_rsqf(ld_agent(rowss + row) * (1.0f / 1024.0f) + 1e-6f); }
; __device__ __forceinline__ unsigned silu_pk(f32x2 g, f32x2 u, float k1, float k2) {
;     const f32x2 t = g * k1; f32x2 ex; ex.x = __builtin_amdgcn_exp2f(t.x); ex.y = __builtin_amdgcn_exp2f(t.y);
;     const f32x2 d = ex + 1.0f; f32x2 r; r.x = __builtin_amdgcn_rcpf(d.x); r.y = __builtin_amdgcn_rcpf(d.y);
;     const f32x2 o = (g * u) * (r * k2);
;     return cvt_pk_bf16(o.x, o.y);
; }
; __device__ __forceinline__ float silu_mul(float g, float u) { return g * __builtin_amdgcn_rcpf(1.0f + __builtin_amdgcn_exp2f(-1.4426950408889634f * g)) * u; }
;     __device__ __forceinline__ void operator()(const f32x4 (&acc)[2][2][4][2], const Unit& u, int wr, int wc, int fr, int fq) const {
;         const int row0 = u.pm * BM + wr * 64 + fr, col0 = u.pn * HALF + wc * 32 + 8 * fq;
;         float ssq[2][4];
; #pragma unroll
;         for (int ai = 0; ai < 2; ++ai)
; #pragma unroll
;             for (int m = 0; m < 4; ++m) ssq[ai][m] = ld_agent(rowss + row0 + ai * HALF + m * 16);
; #pragma unroll
;         for (int ai = 0; ai < 2; ++ai)
; #pragma unroll
;             for (int m = 0; m < 4; ++m) {
;                 const int row = row0 + ai * HALF + m * 16; const float rs = __builtin_amdgcn_rsqf(ssq[ai][m] * (1.0f / 1024.0f) + 1e-6f);
;                 const float k1 = -1.4426950408889634f * rs, k2 = rs * rs;
;                 u32x4 w;
; #pragma unroll
;                 for (int n = 0; n < 2; ++n) {
;                     const f32x4 gv = acc[ai][0][m][n], uv = acc[ai][1][m][n];
;                     const unsigned lo = silu_pk((f32x2){gv[0], gv[1]}, (f32x2){uv[0], uv[1]}, k1, k2), hi = silu_pk((f32x2){gv[2], gv[3]}, (f32x2){uv[2], uv[3]}, k1, k2);
;                     if (n == 0) { w.x = lo; w.y = hi; } else { w.z = lo; w.w = hi; }
;                 }
;                 *(u32x4*)(O + (size_t)row * ldc + col0) = w;
.LBB0_1197:
	v_lshl_add_u32 v144, s36, 8, v146
	v_ashrrev_i32_e32 v145, 31, v144
	v_lshl_add_u64 v[226:227], v[144:145], 3, s[12:13]
	global_load_dwordx2 v[154:155], v[226:227], off sc1
	global_load_dwordx2 v[156:157], v[226:227], off offset:128 sc1
	global_load_dwordx2 v[158:159], v[226:227], off offset:256 sc1
	global_load_dwordx2 v[160:161], v[226:227], off offset:384 sc1
	global_load_dwordx2 v[162:163], v[226:227], off offset:1024 sc1
	global_load_dwordx2 v[164:165], v[226:227], off offset:1152 sc1
	global_load_dwordx2 v[166:167], v[226:227], off offset:1280 sc1
	global_load_dwordx2 v[168:169], v[226:227], off offset:1408 sc1
	v_pk_mul_f32 v[124:125], v[120:121], v[124:125]
	v_pk_mul_f32 v[126:127], v[122:123], v[126:127]
	v_pk_mul_f32 v[112:113], v[116:117], v[112:113]
	v_pk_mul_f32 v[114:115], v[118:119], v[114:115]
	v_pk_mul_f32 v[104:105], v[108:109], v[104:105]
	v_pk_mul_f32 v[106:107], v[110:111], v[106:107]
	v_pk_mul_f32 v[96:97], v[100:101], v[96:97]
	v_pk_mul_f32 v[98:99], v[102:103], v[98:99]
	v_pk_mul_f32 v[88:89], v[92:93], v[88:89]
	v_pk_mul_f32 v[90:91], v[94:95], v[90:91]
	v_pk_mul_f32 v[80:81], v[84:85], v[80:81]
	v_pk_mul_f32 v[82:83], v[86:87], v[82:83]
	v_pk_mul_f32 v[72:73], v[76:77], v[72:73]
	v_pk_mul_f32 v[74:75], v[78:79], v[74:75]
	v_pk_mul_f32 v[64:65], v[68:69], v[64:65]
	v_pk_mul_f32 v[66:67], v[70:71], v[66:67]
	v_pk_mul_f32 v[56:57], v[60:61], v[56:57]
	v_pk_mul_f32 v[58:59], v[62:63], v[58:59]
	v_pk_mul_f32 v[48:49], v[52:53], v[48:49]
	v_pk_mul_f32 v[50:51], v[54:55], v[50:51]
	v_pk_mul_f32 v[40:41], v[44:45], v[40:41]
	v_pk_mul_f32 v[42:43], v[46:47], v[42:43]
	v_pk_mul_f32 v[32:33], v[36:37], v[32:33]
	v_pk_mul_f32 v[34:35], v[38:39], v[34:35]
	v_pk_mul_f32 v[24:25], v[28:29], v[24:25]
	v_pk_mul_f32 v[26:27], v[30:31], v[26:27]
	v_pk_mul_f32 v[16:17], v[20:21], v[16:17]
	v_pk_mul_f32 v[18:19], v[22:23], v[18:19]
	v_pk_mul_f32 v[8:9], v[12:13], v[8:9]
	v_pk_mul_f32 v[10:11], v[14:15], v[10:11]
	v_pk_mul_f32 v[0:1], v[4:5], v[0:1]
	v_pk_mul_f32 v[2:3], v[6:7], v[2:3]
	v_lshl_or_b32 v230, s63, 7, v148
	v_ashrrev_i32_e32 v231, 31, v230
	v_mov_b64_e32 v[232:233], s[8:9]
	v_lshlrev_b64 v[230:231], 1, v[230:231]
	v_mad_i64_i32 v[228:229], s[38:39], v144, s59, v[232:233]
	s_mov_b64 s[96:97], 0x16000
	s_mov_b64 s[98:99], 0x6e000
	v_lshl_add_u64 v[228:229], v[228:229], 0, v[230:231]
	s_andn2_b64 vcc, exec, s[4:5]
	s_mov_b64 s[4:5], -1
	s_waitcnt vmcnt(0)
	v_cvt_f32_u32_e32 v186, v155
	v_cvt_f32_u32_e32 v188, v157
	v_cvt_f32_u32_e32 v190, v159
	v_cvt_f32_u32_e32 v192, v161
	v_cvt_f32_u32_e32 v194, v163
	v_cvt_f32_u32_e32 v196, v165
	v_cvt_f32_u32_e32 v198, v167
	v_cvt_f32_u32_e32 v200, v169
	v_cvt_f32_u32_e32 v187, v154
	v_cvt_f32_u32_e32 v189, v156
	v_cvt_f32_u32_e32 v191, v158
	v_cvt_f32_u32_e32 v193, v160
	v_cvt_f32_u32_e32 v195, v162
	v_cvt_f32_u32_e32 v197, v164
	v_cvt_f32_u32_e32 v199, v166
	v_cvt_f32_u32_e32 v201, v168
	v_fmamk_f32 v186, v186, 0x4f800000, v187
	v_fmamk_f32 v188, v188, 0x4f800000, v189
	v_fmamk_f32 v190, v190, 0x4f800000, v191
	v_fmamk_f32 v192, v192, 0x4f800000, v193
	v_fmamk_f32 v194, v194, 0x4f800000, v195
	v_fmamk_f32 v196, v196, 0x4f800000, v197
	v_fmamk_f32 v198, v198, 0x4f800000, v199
	v_fmamk_f32 v200, v200, 0x4f800000, v201
	v_fmamk_f32 v171, v186, 0x2e800000, v152
	v_fmamk_f32 v173, v188, 0x2e800000, v152
	v_fmamk_f32 v175, v190, 0x2e800000, v152
	v_fmamk_f32 v177, v192, 0x2e800000, v152
	v_fmamk_f32 v179, v194, 0x2e800000, v152
	v_fmamk_f32 v181, v196, 0x2e800000, v152
	v_fmamk_f32 v183, v198, 0x2e800000, v152
	v_fmamk_f32 v185, v200, 0x2e800000, v152
	v_rsq_f32_e32 v170, v171
	v_rsq_f32_e32 v172, v173
	v_rsq_f32_e32 v174, v175
	v_rsq_f32_e32 v176, v177
	v_rsq_f32_e32 v178, v179
	v_rsq_f32_e32 v180, v181
	v_rsq_f32_e32 v182, v183
	v_rsq_f32_e32 v184, v185
	v_mul_f32_e32 v170, 0xbfb8aa3b, v170
	v_mul_f32_e32 v172, 0xbfb8aa3b, v172
	v_mul_f32_e32 v174, 0xbfb8aa3b, v174
	v_mul_f32_e32 v176, 0xbfb8aa3b, v176
	v_mul_f32_e32 v178, 0xbfb8aa3b, v178
	v_mul_f32_e32 v180, 0xbfb8aa3b, v180
	v_mul_f32_e32 v182, 0xbfb8aa3b, v182
	v_mul_f32_e32 v184, 0xbfb8aa3b, v184
	v_pk_mul_f32 v[186:187], v[120:121], v[170:171] op_sel_hi:[1,0]
	v_pk_mul_f32 v[188:189], v[122:123], v[170:171] op_sel_hi:[1,0]
	v_pk_mul_f32 v[190:191], v[116:117], v[170:171] op_sel_hi:[1,0]
	v_pk_mul_f32 v[192:193], v[118:119], v[170:171] op_sel_hi:[1,0]
	v_exp_f32_e32 v186, v186
	v_exp_f32_e32 v187, v187
	v_exp_f32_e32 v188, v188
	v_exp_f32_e32 v189, v189
	v_exp_f32_e32 v190, v190
	v_exp_f32_e32 v191, v191
	v_exp_f32_e32 v192, v192
	v_exp_f32_e32 v193, v193
	v_pk_mul_f32 v[194:195], v[108:109], v[172:173] op_sel_hi:[1,0]
	v_pk_mul_f32 v[196:197], v[110:111], v[172:173] op_sel_hi:[1,0]
	v_pk_mul_f32 v[198:199], v[100:101], v[172:173] op_sel_hi:[1,0]
	v_pk_mul_f32 v[200:201], v[102:103], v[172:173] op_sel_hi:[1,0]
	v_exp_f32_e32 v194, v194
	v_pk_fma_f32 v[186:187], v[186:187], v[170:171], v[170:171] op_sel:[0,1,1] op_sel_hi:[1,1,1]
	v_exp_f32_e32 v195, v195
	v_pk_fma_f32 v[188:189], v[188:189], v[170:171], v[170:171] op_sel:[0,1,1] op_sel_hi:[1,1,1]
	v_exp_f32_e32 v196, v196
	v_pk_fma_f32 v[190:191], v[190:191], v[170:171], v[170:171] op_sel:[0,1,1] op_sel_hi:[1,1,1]
	v_exp_f32_e32 v197, v197
	v_pk_fma_f32 v[192:193], v[192:193], v[170:171], v[170:171] op_sel:[0,1,1] op_sel_hi:[1,1,1]
	v_exp_f32_e32 v198, v198
	v_exp_f32_e32 v199, v199
	v_exp_f32_e32 v200, v200
	v_exp_f32_e32 v201, v201
	v_rcp_f32_e32 v186, v186
	v_pk_mul_f32 v[202:203], v[92:93], v[174:175] op_sel_hi:[1,0]
	v_rcp_f32_e32 v187, v187
	v_pk_mul_f32 v[204:205], v[94:95], v[174:175] op_sel_hi:[1,0]
	v_rcp_f32_e32 v188, v188
	v_pk_mul_f32 v[206:207], v[84:85], v[174:175] op_sel_hi:[1,0]
; __device__ __forceinline__ unsigned cvt_pk_bf16(float lo, float hi) { unsigned r; asm volatile("v_cvt_pk_bf16_f32 %0, %1, %2" : "=v"(r) : "v"(lo), "v"(hi)); return r; }
; __device__ __forceinline__ unsigned silu_pk(f32x2 g, f32x2 u, float k1, float k2) {
;     const f32x2 t = g * k1; f32x2 ex; ex.x = __builtin_amdgcn_exp2f(t.x); ex.y = __builtin_amdgcn_exp2f(t.y);
;     const f32x2 d = ex + 1.0f; f32x2 r; r.x = __builtin_amdgcn_rcpf(d.x); r.y = __builtin_amdgcn_rcpf(d.y);
;     const f32x2 o = (g * u) * (r * k2);
;     return cvt_pk_bf16(o.x, o.y);
;     __device__ __forceinline__ void operator()(const f32x4 (&acc)[2][2][4][2], const Unit& u, int wr, int wc, int fr, int fq) const {
;     ...
;             for (int m = 0; m < 4; ++m) {
;                 const int row = row0 + ai * HALF + m * 16; const float rs = __builtin_amdgcn_rsqf(ssq[ai][m] * (1.0f / 1024.0f) + 1e-6f);
;                 const float k1 = -1.4426950408889634f * rs, k2 = rs * rs;
;                 u32x4 w;
; #pragma unroll
;                 for (int n = 0; n < 2; ++n) {
;                     const f32x4 gv = acc[ai][0][m][n], uv = acc[ai][1][m][n];
;                     const unsigned lo = silu_pk((f32x2){gv[0], gv[1]}, (f32x2){uv[0], uv[1]}, k1, k2), hi = silu_pk((f32x2){gv[2], gv[3]}, (f32x2){uv[2], uv[3]}, k1, k2);
;                     if (n == 0) { w.x = lo; w.y = hi; } else { w.z = lo; w.w = hi; }
;                 }
;                 *(u32x4*)(O + (size_t)row * ldc + col0) = w;
	v_rcp_f32_e32 v189, v189
	v_pk_mul_f32 v[208:209], v[86:87], v[174:175] op_sel_hi:[1,0]
	v_rcp_f32_e32 v190, v190
	v_rcp_f32_e32 v191, v191
	v_rcp_f32_e32 v192, v192
	v_rcp_f32_e32 v193, v193
	v_exp_f32_e32 v202, v202
	v_pk_fma_f32 v[194:195], v[194:195], v[172:173], v[172:173] op_sel:[0,1,1] op_sel_hi:[1,1,1]
	v_exp_f32_e32 v203, v203
	v_pk_fma_f32 v[196:197], v[196:197], v[172:173], v[172:173] op_sel:[0,1,1] op_sel_hi:[1,1,1]
	v_exp_f32_e32 v204, v204
	v_pk_fma_f32 v[198:199], v[198:199], v[172:173], v[172:173] op_sel:[0,1,1] op_sel_hi:[1,1,1]
	v_exp_f32_e32 v205, v205
	v_pk_fma_f32 v[200:201], v[200:201], v[172:173], v[172:173] op_sel:[0,1,1] op_sel_hi:[1,1,1]
	v_exp_f32_e32 v206, v206
	v_pk_mul_f32 v[186:187], v[124:125], v[186:187]
	v_exp_f32_e32 v207, v207
	v_pk_mul_f32 v[188:189], v[126:127], v[188:189]
	v_exp_f32_e32 v208, v208
	v_pk_mul_f32 v[190:191], v[112:113], v[190:191]
	v_exp_f32_e32 v209, v209
	v_pk_mul_f32 v[192:193], v[114:115], v[192:193]
	v_rcp_f32_e32 v194, v194
	v_cvt_pk_bf16_f32 v218, v186, v187
	v_rcp_f32_e32 v195, v195
	v_cvt_pk_bf16_f32 v219, v188, v189
	v_rcp_f32_e32 v196, v196
	v_cvt_pk_bf16_f32 v220, v190, v191
	v_rcp_f32_e32 v197, v197
	v_cvt_pk_bf16_f32 v221, v192, v193
	v_rcp_f32_e32 v198, v198
	global_store_dwordx4 v[228:229], v[218:221], off
	v_rcp_f32_e32 v199, v199
	v_lshl_add_u64 v[228:229], v[228:229], 0, s[96:97]
	v_rcp_f32_e32 v200, v200
	v_pk_mul_f32 v[210:211], v[76:77], v[176:177] op_sel_hi:[1,0]
	v_rcp_f32_e32 v201, v201
	v_pk_mul_f32 v[212:213], v[78:79], v[176:177] op_sel_hi:[1,0]
	v_pk_mul_f32 v[214:215], v[68:69], v[176:177] op_sel_hi:[1,0]
	v_pk_mul_f32 v[216:217], v[70:71], v[176:177] op_sel_hi:[1,0]
	v_exp_f32_e32 v210, v210
	v_pk_fma_f32 v[202:203], v[202:203], v[174:175], v[174:175] op_sel:[0,1,1] op_sel_hi:[1,1,1]
	v_exp_f32_e32 v211, v211
	v_pk_fma_f32 v[204:205], v[204:205], v[174:175], v[174:175] op_sel:[0,1,1] op_sel_hi:[1,1,1]
	v_exp_f32_e32 v212, v212
	v_pk_fma_f32 v[206:207], v[206:207], v[174:175], v[174:175] op_sel:[0,1,1] op_sel_hi:[1,1,1]
	v_exp_f32_e32 v213, v213
	v_pk_fma_f32 v[208:209], v[208:209], v[174:175], v[174:175] op_sel:[0,1,1] op_sel_hi:[1,1,1]
	v_exp_f32_e32 v214, v214
	v_pk_mul_f32 v[194:195], v[104:105], v[194:195]
	v_exp_f32_e32 v215, v215
	v_pk_mul_f32 v[196:197], v[106:107], v[196:197]
	v_exp_f32_e32 v216, v216
	v_pk_mul_f32 v[198:199], v[96:97], v[198:199]
	v_exp_f32_e32 v217, v217
	v_pk_mul_f32 v[200:201], v[98:99], v[200:201]
	v_rcp_f32_e32 v202, v202
	v_cvt_pk_bf16_f32 v222, v194, v195
	v_rcp_f32_e32 v203, v203
	v_cvt_pk_bf16_f32 v223, v196, v197
	v_rcp_f32_e32 v204, v204
	v_cvt_pk_bf16_f32 v224, v198, v199
	v_rcp_f32_e32 v205, v205
	v_cvt_pk_bf16_f32 v225, v200, v201
	v_rcp_f32_e32 v206, v206
	global_store_dwordx4 v[228:229], v[222:225], off
	v_rcp_f32_e32 v207, v207
	v_lshl_add_u64 v[228:229], v[228:229], 0, s[96:97]
	v_rcp_f32_e32 v208, v208
	v_pk_mul_f32 v[186:187], v[60:61], v[178:179] op_sel_hi:[1,0]
	v_rcp_f32_e32 v209, v209
	v_pk_mul_f32 v[188:189], v[62:63], v[178:179] op_sel_hi:[1,0]
	v_pk_mul_f32 v[190:191], v[52:53], v[178:179] op_sel_hi:[1,0]
	v_pk_mul_f32 v[192:193], v[54:55], v[178:179] op_sel_hi:[1,0]
	v_exp_f32_e32 v186, v186
	v_pk_fma_f32 v[210:211], v[210:211], v[176:177], v[176:177] op_sel:[0,1,1] op_sel_hi:[1,1,1]
	v_exp_f32_e32 v187, v187
	v_pk_fma_f32 v[212:213], v[212:213], v[176:177], v[176:177] op_sel:[0,1,1] op_sel_hi:[1,1,1]
	v_exp_f32_e32 v188, v188
	v_pk_fma_f32 v[214:215], v[214:215], v[176:177], v[176:177] op_sel:[0,1,1] op_sel_hi:[1,1,1]
	v_exp_f32_e32 v189, v189
	v_pk_fma_f32 v[216:217], v[216:217], v[176:177], v[176:177] op_sel:[0,1,1] op_sel_hi:[1,1,1]
	v_exp_f32_e32 v190, v190
	v_pk_mul_f32 v[202:203], v[88:89], v[202:203]
	v_exp_f32_e32 v191, v191
	v_pk_mul_f32 v[204:205], v[90:91], v[204:205]
	v_exp_f32_e32 v192, v192
	v_pk_mul_f32 v[206:207], v[80:81], v[206:207]
	v_exp_f32_e32 v193, v193
	v_pk_mul_f32 v[208:209], v[82:83], v[208:209]
	v_rcp_f32_e32 v210, v210
	v_cvt_pk_bf16_f32 v218, v202, v203
	v_rcp_f32_e32 v211, v211
	v_cvt_pk_bf16_f32 v219, v204, v205
	v_rcp_f32_e32 v212, v212
	v_cvt_pk_bf16_f32 v220, v206, v207
	v_rcp_f32_e32 v213, v213
	v_cvt_pk_bf16_f32 v221, v208, v209
	v_rcp_f32_e32 v214, v214
	global_store_dwordx4 v[228:229], v[218:221], off
	v_rcp_f32_e32 v215, v215
	v_lshl_add_u64 v[228:229], v[228:229], 0, s[96:97]
	v_rcp_f32_e32 v216, v216
	v_pk_mul_f32 v[194:195], v[44:45], v[180:181] op_sel_hi:[1,0]
	v_rcp_f32_e32 v217, v217
	v_pk_mul_f32 v[196:197], v[46:47], v[180:181] op_sel_hi:[1,0]
	v_pk_mul_f32 v[198:199], v[36:37], v[180:181] op_sel_hi:[1,0]
	v_pk_mul_f32 v[200:201], v[38:39], v[180:181] op_sel_hi:[1,0]
	v_exp_f32_e32 v194, v194
	v_pk_fma_f32 v[186:187], v[186:187], v[178:179], v[178:179] op_sel:[0,1,1] op_sel_hi:[1,1,1]
	v_exp_f32_e32 v195, v195
	v_pk_fma_f32 v[188:189], v[188:189], v[178:179], v[178:179] op_sel:[0,1,1] op_sel_hi:[1,1,1]
	v_exp_f32_e32 v196, v196
	v_pk_fma_f32 v[190:191], v[190:191], v[178:179], v[178:179] op_sel:[0,1,1] op_sel_hi:[1,1,1]
	v_exp_f32_e32 v197, v197
	v_pk_fma_f32 v[192:193], v[192:193], v[178:179], v[178:179] op_sel:[0,1,1] op_sel_hi:[1,1,1]
	v_exp_f32_e32 v198, v198
; __device__ __forceinline__ unsigned cvt_pk_bf16(float lo, float hi) { unsigned r; asm volatile("v_cvt_pk_bf16_f32 %0, %1, %2" : "=v"(r) : "v"(lo), "v"(hi)); return r; }
; #define PG8_BAR __builtin_amdgcn_s_barrier()
; __device__ __forceinline__ unsigned silu_pk(f32x2 g, f32x2 u, float k1, float k2) {
;     const f32x2 t = g * k1; f32x2 ex; ex.x = __builtin_amdgcn_exp2f(t.x); ex.y = __builtin_amdgcn_exp2f(t.y);
;     const f32x2 d = ex + 1.0f; f32x2 r; r.x = __builtin_amdgcn_rcpf(d.x); r.y = __builtin_amdgcn_rcpf(d.y);
;     const f32x2 o = (g * u) * (r * k2);
;     return cvt_pk_bf16(o.x, o.y);
;     __device__ __forceinline__ void operator()(const f32x4 (&acc)[2][2][4][2], const Unit& u, int wr, int wc, int fr, int fq) const {
;     ...
;             for (int m = 0; m < 4; ++m) {
;                 const int row = row0 + ai * HALF + m * 16; const float rs = __builtin_amdgcn_rsqf(ssq[ai][m] * (1.0f / 1024.0f) + 1e-6f);
;                 const float k1 = -1.4426950408889634f * rs, k2 = rs * rs;
;                 u32x4 w;
; #pragma unroll
;                 for (int n = 0; n < 2; ++n) {
;                     const f32x4 gv = acc[ai][0][m][n], uv = acc[ai][1][m][n];
;                     const unsigned lo = silu_pk((f32x2){gv[0], gv[1]}, (f32x2){uv[0], uv[1]}, k1, k2), hi = silu_pk((f32x2){gv[2], gv[3]}, (f32x2){uv[2], uv[3]}, k1, k2);
;                     if (n == 0) { w.x = lo; w.y = hi; } else { w.z = lo; w.w = hi; }
;                 }
;                 *(u32x4*)(O + (size_t)row * ldc + col0) = w;
; template <class Epi, class Sched, bool ALIGN_EPI = false, bool SP2 = false>
; __device__ __forceinline__ void gemm_phase(PG8_LAS unsigned char* lds, const Gemm g, const Sched& S, const Epi& E) {
;     ...
;         if constexpr (ALIGN_EPI) { if (wr == 1) PG8_BAR; }
	v_pk_mul_f32 v[210:211], v[72:73], v[210:211]
	v_exp_f32_e32 v199, v199
	v_pk_mul_f32 v[212:213], v[74:75], v[212:213]
	v_exp_f32_e32 v200, v200
	v_pk_mul_f32 v[214:215], v[64:65], v[214:215]
	v_exp_f32_e32 v201, v201
	v_pk_mul_f32 v[216:217], v[66:67], v[216:217]
	v_rcp_f32_e32 v186, v186
	v_cvt_pk_bf16_f32 v222, v210, v211
	v_rcp_f32_e32 v187, v187
	v_cvt_pk_bf16_f32 v223, v212, v213
	v_rcp_f32_e32 v188, v188
	v_cvt_pk_bf16_f32 v224, v214, v215
	v_rcp_f32_e32 v189, v189
	v_cvt_pk_bf16_f32 v225, v216, v217
	v_rcp_f32_e32 v190, v190
	global_store_dwordx4 v[228:229], v[222:225], off
	v_rcp_f32_e32 v191, v191
	v_lshl_add_u64 v[228:229], v[228:229], 0, s[98:99]
	v_rcp_f32_e32 v192, v192
	v_pk_mul_f32 v[202:203], v[28:29], v[182:183] op_sel_hi:[1,0]
	v_rcp_f32_e32 v193, v193
	v_pk_mul_f32 v[204:205], v[30:31], v[182:183] op_sel_hi:[1,0]
	v_pk_mul_f32 v[206:207], v[20:21], v[182:183] op_sel_hi:[1,0]
	v_pk_mul_f32 v[208:209], v[22:23], v[182:183] op_sel_hi:[1,0]
	v_exp_f32_e32 v202, v202
	v_pk_fma_f32 v[194:195], v[194:195], v[180:181], v[180:181] op_sel:[0,1,1] op_sel_hi:[1,1,1]
	v_exp_f32_e32 v203, v203
	v_pk_fma_f32 v[196:197], v[196:197], v[180:181], v[180:181] op_sel:[0,1,1] op_sel_hi:[1,1,1]
	v_exp_f32_e32 v204, v204
	v_pk_fma_f32 v[198:199], v[198:199], v[180:181], v[180:181] op_sel:[0,1,1] op_sel_hi:[1,1,1]
	v_exp_f32_e32 v205, v205
	v_pk_fma_f32 v[200:201], v[200:201], v[180:181], v[180:181] op_sel:[0,1,1] op_sel_hi:[1,1,1]
	v_exp_f32_e32 v206, v206
	v_pk_mul_f32 v[186:187], v[56:57], v[186:187]
	v_exp_f32_e32 v207, v207
	v_pk_mul_f32 v[188:189], v[58:59], v[188:189]
	v_exp_f32_e32 v208, v208
	v_pk_mul_f32 v[190:191], v[48:49], v[190:191]
	v_exp_f32_e32 v209, v209
	v_pk_mul_f32 v[192:193], v[50:51], v[192:193]
	v_rcp_f32_e32 v194, v194
	v_cvt_pk_bf16_f32 v218, v186, v187
	v_rcp_f32_e32 v195, v195
	v_cvt_pk_bf16_f32 v219, v188, v189
	v_rcp_f32_e32 v196, v196
	v_cvt_pk_bf16_f32 v220, v190, v191
	v_rcp_f32_e32 v197, v197
	v_cvt_pk_bf16_f32 v221, v192, v193
	v_rcp_f32_e32 v198, v198
	global_store_dwordx4 v[228:229], v[218:221], off
	v_rcp_f32_e32 v199, v199
	v_lshl_add_u64 v[228:229], v[228:229], 0, s[96:97]
	v_rcp_f32_e32 v200, v200
	v_pk_mul_f32 v[210:211], v[12:13], v[184:185] op_sel_hi:[1,0]
	v_rcp_f32_e32 v201, v201
	v_pk_mul_f32 v[212:213], v[14:15], v[184:185] op_sel_hi:[1,0]
	v_pk_mul_f32 v[214:215], v[4:5], v[184:185] op_sel_hi:[1,0]
	v_pk_mul_f32 v[216:217], v[6:7], v[184:185] op_sel_hi:[1,0]
	v_exp_f32_e32 v210, v210
	v_pk_fma_f32 v[202:203], v[202:203], v[182:183], v[182:183] op_sel:[0,1,1] op_sel_hi:[1,1,1]
	v_exp_f32_e32 v211, v211
	v_pk_fma_f32 v[204:205], v[204:205], v[182:183], v[182:183] op_sel:[0,1,1] op_sel_hi:[1,1,1]
	v_exp_f32_e32 v212, v212
	v_pk_fma_f32 v[206:207], v[206:207], v[182:183], v[182:183] op_sel:[0,1,1] op_sel_hi:[1,1,1]
	v_exp_f32_e32 v213, v213
	v_pk_fma_f32 v[208:209], v[208:209], v[182:183], v[182:183] op_sel:[0,1,1] op_sel_hi:[1,1,1]
	v_exp_f32_e32 v214, v214
	v_pk_mul_f32 v[194:195], v[40:41], v[194:195]
	v_exp_f32_e32 v215, v215
	v_pk_mul_f32 v[196:197], v[42:43], v[196:197]
	v_exp_f32_e32 v216, v216
	v_pk_mul_f32 v[198:199], v[32:33], v[198:199]
	v_exp_f32_e32 v217, v217
	v_pk_mul_f32 v[200:201], v[34:35], v[200:201]
	v_rcp_f32_e32 v202, v202
	v_cvt_pk_bf16_f32 v222, v194, v195
	v_rcp_f32_e32 v203, v203
	v_cvt_pk_bf16_f32 v223, v196, v197
	v_rcp_f32_e32 v204, v204
	v_cvt_pk_bf16_f32 v224, v198, v199
	v_rcp_f32_e32 v205, v205
	v_cvt_pk_bf16_f32 v225, v200, v201
	v_rcp_f32_e32 v206, v206
	global_store_dwordx4 v[228:229], v[222:225], off
	v_rcp_f32_e32 v207, v207
	v_lshl_add_u64 v[228:229], v[228:229], 0, s[96:97]
	v_rcp_f32_e32 v208, v208
	v_rcp_f32_e32 v209, v209
	v_pk_fma_f32 v[210:211], v[210:211], v[184:185], v[184:185] op_sel:[0,1,1] op_sel_hi:[1,1,1]
	v_pk_fma_f32 v[212:213], v[212:213], v[184:185], v[184:185] op_sel:[0,1,1] op_sel_hi:[1,1,1]
	v_pk_fma_f32 v[214:215], v[214:215], v[184:185], v[184:185] op_sel:[0,1,1] op_sel_hi:[1,1,1]
	v_pk_fma_f32 v[216:217], v[216:217], v[184:185], v[184:185] op_sel:[0,1,1] op_sel_hi:[1,1,1]
	v_pk_mul_f32 v[202:203], v[24:25], v[202:203]
	v_pk_mul_f32 v[204:205], v[26:27], v[204:205]
	v_pk_mul_f32 v[206:207], v[16:17], v[206:207]
	v_pk_mul_f32 v[208:209], v[18:19], v[208:209]
	v_rcp_f32_e32 v210, v210
	v_cvt_pk_bf16_f32 v218, v202, v203
	v_rcp_f32_e32 v211, v211
	v_cvt_pk_bf16_f32 v219, v204, v205
	v_rcp_f32_e32 v212, v212
	v_cvt_pk_bf16_f32 v220, v206, v207
	v_rcp_f32_e32 v213, v213
	v_cvt_pk_bf16_f32 v221, v208, v209
	v_rcp_f32_e32 v214, v214
	global_store_dwordx4 v[228:229], v[218:221], off
	v_rcp_f32_e32 v215, v215
	v_lshl_add_u64 v[228:229], v[228:229], 0, s[96:97]
	v_rcp_f32_e32 v216, v216
	v_rcp_f32_e32 v217, v217
	v_pk_mul_f32 v[210:211], v[8:9], v[210:211]
	v_pk_mul_f32 v[212:213], v[10:11], v[212:213]
	v_pk_mul_f32 v[214:215], v[0:1], v[214:215]
	v_pk_mul_f32 v[216:217], v[2:3], v[216:217]
	v_cvt_pk_bf16_f32 v222, v210, v211
	v_cvt_pk_bf16_f32 v223, v212, v213
	v_cvt_pk_bf16_f32 v224, v214, v215
	v_cvt_pk_bf16_f32 v225, v216, v217
	global_store_dwordx4 v[228:229], v[222:225], off
	s_cbranch_vccnz .LBB0_1190
	s_andn2_b64 vcc, exec, s[6:7]
	s_cbranch_vccnz .LBB0_1189
	s_barrier
	s_branch .LBB0_1189
